# v26 plus the 48 packed v_pk_mul_f32 (O rescale by alpha) in the attention chunk loops split into scalar v_mul_f32 pairs (packed fp32 beside MFMAs is priced above two singles)
# baseline (speedup 1.0000x reference)
.LBB0_1245:
	v_add_u32_e32 v36, v127, v129
	ds_read_b128 v[32:35], v36
	ds_read_b128 v[108:111], v36 offset:32
	ds_read_b128 v[112:115], v36 offset:64
	ds_read_b128 v[116:119], v36 offset:96
	v_add_u32_e32 v107, 27, v104
	s_waitcnt lgkmcnt(3)
	v_mfma_f32_32x32x16_bf16 v[32:47], v[32:35], v[48:51], 0
	v_cmp_lt_i32_e32 vcc, -1, v103
	v_cmp_le_u32_e64 s[8:9], v107, v100
	s_and_b64 vcc, vcc, s[8:9]
	v_add_u32_e32 v107, 26, v104
	v_cmp_le_u32_e64 s[8:9], v107, v100
	v_add_u32_e32 v102, s18, v102
	s_waitcnt lgkmcnt(2)
	v_mfma_f32_32x32x16_bf16 v[32:47], v[108:111], v[52:55], v[32:47]
	v_add_u32_e32 v108, 25, v104
	s_waitcnt lgkmcnt(1)
	v_mfma_f32_32x32x16_bf16 v[32:47], v[112:115], v[56:59], v[32:47]
	s_waitcnt lgkmcnt(0)
	v_mfma_f32_32x32x16_bf16 v[32:47], v[116:119], v[60:63], v[32:47]
	s_nop 11
	v_cndmask_b32_e32 v32, v173, v32, vcc
	v_cmp_lt_i32_e32 vcc, -2, v103
	s_and_b64 vcc, vcc, s[8:9]
	v_cmp_le_u32_e64 s[8:9], v108, v100
	v_cndmask_b32_e32 v33, v173, v33, vcc
	v_cmp_lt_i32_e32 vcc, -3, v103
	s_and_b64 vcc, vcc, s[8:9]
	v_add_u32_e32 v108, 24, v104
	v_cndmask_b32_e32 v34, v173, v34, vcc
	v_cmp_lt_i32_e32 vcc, -4, v103
	v_cmp_le_u32_e64 s[8:9], v108, v100
	s_and_b64 vcc, vcc, s[8:9]
	v_add_u32_e32 v108, 19, v104
	v_cndmask_b32_e32 v35, v173, v35, vcc
	v_cmp_lt_i32_e32 vcc, -9, v103
	v_cmp_le_u32_e64 s[8:9], v108, v100
	s_and_b64 vcc, vcc, s[8:9]
	v_add_u32_e32 v108, 18, v104
	v_cndmask_b32_e32 v36, v173, v36, vcc
	v_cmp_lt_i32_e32 vcc, -10, v103
	v_cmp_le_u32_e64 s[8:9], v108, v100
	s_and_b64 vcc, vcc, s[8:9]
	v_add_u32_e32 v108, 17, v104
	v_cndmask_b32_e32 v37, v173, v37, vcc
	v_cmp_lt_i32_e32 vcc, -11, v103
	v_cmp_le_u32_e64 s[8:9], v108, v100
	s_and_b64 vcc, vcc, s[8:9]
	v_add_u32_e32 v108, 16, v104
	v_cndmask_b32_e32 v38, v173, v38, vcc
	v_cmp_lt_i32_e32 vcc, -12, v103
	v_cmp_le_u32_e64 s[8:9], v108, v100
	s_and_b64 vcc, vcc, s[8:9]
	v_add_u32_e32 v108, 11, v104
	s_movk_i32 s8, 0xffef
	v_cndmask_b32_e32 v39, v173, v39, vcc
	v_cmp_lt_i32_e32 vcc, s8, v103
	v_cmp_le_u32_e64 s[8:9], v108, v100
	s_and_b64 vcc, vcc, s[8:9]
	v_max3_f32 v107, v32, s90, v33
	v_cndmask_b32_e32 v108, v173, v40, vcc
	v_add_u32_e32 v40, 10, v104
	s_movk_i32 s8, 0xffee
	v_max3_f32 v107, v107, v34, v35
	v_cmp_lt_i32_e32 vcc, s8, v103
	v_cmp_le_u32_e64 s[8:9], v40, v100
	v_max3_f32 v107, v107, v36, v37
	s_and_b64 vcc, vcc, s[8:9]
	v_max3_f32 v107, v107, v38, v39
	v_cndmask_b32_e32 v41, v173, v41, vcc
	v_max3_f32 v40, v107, v108, v41
	v_add_u32_e32 v107, 9, v104
	s_movk_i32 s8, 0xffed
	v_cmp_lt_i32_e32 vcc, s8, v103
	v_cmp_le_u32_e64 s[8:9], v107, v100
	s_and_b64 vcc, vcc, s[8:9]
	v_add_u32_e32 v107, 8, v104
	s_movk_i32 s8, 0xffec
	v_cndmask_b32_e32 v42, v173, v42, vcc
	v_cmp_lt_i32_e32 vcc, s8, v103
	v_cmp_le_u32_e64 s[8:9], v107, v100
	s_and_b64 vcc, vcc, s[8:9]
	v_add_u32_e32 v107, 3, v104
	s_movk_i32 s8, 0xffe7
	v_cndmask_b32_e32 v43, v173, v43, vcc
	v_cmp_lt_i32_e32 vcc, s8, v103
	v_cmp_le_u32_e64 s[8:9], v107, v100
	s_and_b64 vcc, vcc, s[8:9]
	v_add_u32_e32 v107, 2, v104
	s_movk_i32 s8, 0xffe6
	v_cndmask_b32_e32 v44, v173, v44, vcc
	v_cmp_lt_i32_e32 vcc, s8, v103
	v_cmp_le_u32_e64 s[8:9], v107, v100
	s_and_b64 vcc, vcc, s[8:9]
	v_add_u32_e32 v107, 1, v104
	s_movk_i32 s8, 0xffe5
	v_cndmask_b32_e32 v45, v173, v45, vcc
	v_cmp_lt_i32_e32 vcc, s8, v103
	v_cmp_le_u32_e64 s[8:9], v107, v100
	s_and_b64 vcc, vcc, s[8:9]
	s_movk_i32 s8, 0xffe4
	v_cndmask_b32_e32 v46, v173, v46, vcc
	v_cmp_lt_i32_e32 vcc, s8, v103
	v_cmp_le_u32_e64 s[8:9], v104, v100
	v_max3_f32 v40, v40, v42, v43
	s_and_b64 vcc, vcc, s[8:9]
	v_max3_f32 v40, v40, v44, v45
	v_cndmask_b32_e32 v47, v173, v47, vcc
	v_max3_f32 v40, v40, v46, v47
	v_mov_b32_e32 v107, v40
	s_nop 1
	v_permlane32_swap_b32_e32 v107, v40
	v_subrev_u32_e32 v104, 32, v104
	v_add_u32_e32 v103, 32, v103
	s_andn2_b64 vcc, exec, s[80:81]
	s_waitcnt lgkmcnt(0)
	v_max3_f32 v40, v106, v40, v107
	v_sub_f32_e32 v32, v32, v40
	v_exp_f32_e32 v32, v32
	v_sub_f32_e32 v33, v33, v40
	v_exp_f32_e32 v33, v33
	v_sub_f32_e32 v34, v34, v40
	v_exp_f32_e32 v34, v34
	v_sub_f32_e32 v35, v35, v40
	v_exp_f32_e32 v35, v35
	v_sub_f32_e32 v36, v36, v40
	v_add_f32_e32 v107, 0, v32
	v_exp_f32_e32 v109, v36
	v_add_f32_e32 v107, v33, v107
	v_add_f32_e32 v107, v34, v107
	v_add_f32_e32 v107, v35, v107
	v_sub_f32_e32 v37, v37, v40
	v_add_f32_e32 v36, v109, v107
	v_exp_f32_e32 v107, v37
	v_sub_f32_e32 v37, v38, v40
	v_exp_f32_e32 v110, v37
	v_sub_f32_e32 v37, v39, v40
	v_exp_f32_e32 v39, v37
	v_sub_f32_e32 v37, v108, v40
	v_exp_f32_e32 v108, v37
	v_sub_f32_e32 v37, v41, v40
	v_add_f32_e32 v36, v107, v36
	v_exp_f32_e32 v111, v37
	v_sub_f32_e32 v37, v42, v40
	v_add_f32_e32 v36, v110, v36
	v_exp_f32_e32 v42, v37
	v_sub_f32_e32 v37, v43, v40
	v_add_f32_e32 v36, v39, v36
	v_exp_f32_e32 v43, v37
	v_sub_f32_e32 v37, v44, v40
	v_add_f32_e32 v36, v108, v36
	v_exp_f32_e32 v44, v37
	v_sub_f32_e32 v37, v45, v40
	v_add_f32_e32 v36, v111, v36
	v_exp_f32_e32 v45, v37
	v_sub_f32_e32 v37, v46, v40
	v_add_f32_e32 v36, v42, v36
	v_exp_f32_e32 v112, v37
	v_sub_f32_e32 v37, v47, v40
	v_add_f32_e32 v36, v43, v36
	v_exp_f32_e32 v47, v37
	v_add_f32_e32 v36, v44, v36
	v_add_f32_e32 v36, v45, v36
	v_add_f32_e32 v36, v112, v36
	v_add_f32_e32 v36, v47, v36
	v_mov_b32_e32 v37, v36
	s_nop 1
	v_permlane32_swap_b32_e32 v37, v36
	v_sub_f32_e32 v106, v106, v40
	v_exp_f32_e32 v46, v106
	v_cvt_pk_bf16_f32 v38, v109, v107
	v_cvt_pk_bf16_f32 v39, v110, v39
	s_waitcnt lgkmcnt(0)
	v_add_f32_e32 v41, v36, v37
	v_cvt_pk_bf16_f32 v36, v32, v33
	v_cvt_pk_bf16_f32 v37, v34, v35
	v_cvt_pk_bf16_f32 v32, v108, v111
	v_cvt_pk_bf16_f32 v33, v42, v43
	v_cvt_pk_bf16_f32 v34, v44, v45
	v_cvt_pk_bf16_f32 v35, v112, v47
	ds_read_b64_tr_b16 v[42:43], v171 offset:4608
	ds_read_b64_tr_b16 v[44:45], v171 offset:5760
	ds_read_b64_tr_b16 v[106:107], v171 offset:6912
	ds_read_b64_tr_b16 v[108:109], v171 offset:8064
	ds_read_b64_tr_b16 v[110:111], v171 offset:4672
	ds_read_b64_tr_b16 v[112:113], v171 offset:5824
	ds_read_b64_tr_b16 v[114:115], v171 offset:6976
	ds_read_b64_tr_b16 v[116:117], v171 offset:8128
	v_mul_f32_e32 v14, v46, v14
	v_mul_f32_e32 v15, v46, v15
	v_mul_f32_e32 v12, v46, v12
	v_mul_f32_e32 v13, v46, v13
	v_mul_f32_e32 v10, v46, v10
	v_mul_f32_e32 v11, v46, v11
	v_mul_f32_e32 v8, v46, v8
	v_mul_f32_e32 v9, v46, v9
	v_mul_f32_e32 v6, v46, v6
	v_mul_f32_e32 v7, v46, v7
	v_mul_f32_e32 v4, v46, v4
	v_mul_f32_e32 v5, v46, v5
	v_mul_f32_e32 v2, v46, v2
	v_mul_f32_e32 v3, v46, v3
	v_mul_f32_e32 v0, v46, v0
	v_mul_f32_e32 v1, v46, v1
	v_mul_f32_e32 v30, v46, v30
	v_mul_f32_e32 v31, v46, v31
	v_mul_f32_e32 v28, v46, v28
	v_mul_f32_e32 v29, v46, v29
	v_mul_f32_e32 v26, v46, v26
	v_mul_f32_e32 v27, v46, v27
	v_mul_f32_e32 v24, v46, v24
	v_mul_f32_e32 v25, v46, v25
	v_mul_f32_e32 v22, v46, v22
	v_mul_f32_e32 v23, v46, v23
	v_mul_f32_e32 v20, v46, v20
	v_mul_f32_e32 v21, v46, v21
	v_mul_f32_e32 v18, v46, v18
	v_mul_f32_e32 v19, v46, v19
	v_mul_f32_e32 v16, v46, v16
	v_mul_f32_e32 v17, v46, v17
	s_waitcnt lgkmcnt(6)
	v_mfma_f32_32x32x16_bf16 v[0:15], v[42:45], v[36:39], v[0:15]
	v_fmac_f32_e32 v41, v105, v46
	s_waitcnt lgkmcnt(2)
	v_mfma_f32_32x32x16_bf16 v[16:31], v[110:113], v[36:39], v[16:31]
	v_mfma_f32_32x32x16_bf16 v[0:15], v[106:109], v[32:35], v[0:15]
	s_waitcnt lgkmcnt(0)
	v_mfma_f32_32x32x16_bf16 v[16:31], v[114:117], v[32:35], v[16:31]
	s_cbranch_vccz .LBB0_1247
	v_mov_b32_e32 v106, v40
	v_mov_b32_e32 v105, v41
	s_branch .LBB0_1243

.LBB0_1326:
	v_subrev_u32_e32 v32, 28, v182
	v_min_i32_e32 v32, s53, v32
	v_mad_u32_u24 v32, v32, v177, v178
	v_add_u32_e32 v33, -8, v32
	v_cmp_lt_i32_e32 vcc, v32, v180
	v_add_u32_e32 v211, v127, v129
	ds_read_b128 v[216:219], v211 offset:64
	v_cndmask_b32_e32 v32, v33, v32, vcc
	v_mad_u32_u24 v32, v32, v141, v130
	v_mov_b32_e32 v33, 0
	v_cndmask_b32_e32 v35, v145, v149, vcc
	v_cndmask_b32_e32 v34, v144, v148, vcc
	v_lshl_add_u64 v[34:35], v[32:33], 2, v[34:35]
	global_load_dwordx4 v[112:115], v[34:35], off
	v_cndmask_b32_e32 v35, v147, v151, vcc
	v_cndmask_b32_e32 v34, v146, v150, vcc
	v_lshl_add_u64 v[32:33], v[32:33], 2, v[34:35]
	global_load_dwordx4 v[116:119], v[32:33], off
	v_subrev_u32_e32 v32, 24, v182
	v_min_i32_e32 v32, s53, v32
	v_mad_u32_u24 v32, v32, v177, v178
	v_add_u32_e32 v33, -8, v32
	v_cmp_lt_i32_e32 vcc, v32, v180
	v_min_i32_e32 v120, s53, v182
	v_mul_u32_u24_e32 v120, v120, v177
	v_cndmask_b32_e32 v32, v33, v32, vcc
	v_mad_u32_u24 v32, v32, v141, v130
	v_mov_b32_e32 v33, 0
	v_cndmask_b32_e32 v35, v145, v149, vcc
	v_cndmask_b32_e32 v34, v144, v148, vcc
	v_lshl_add_u64 v[34:35], v[32:33], 2, v[34:35]
	global_load_dwordx4 v[104:107], v[34:35], off
	v_cndmask_b32_e32 v35, v147, v151, vcc
	v_cndmask_b32_e32 v34, v146, v150, vcc
	v_lshl_add_u64 v[32:33], v[32:33], 2, v[34:35]
	global_load_dwordx4 v[108:111], v[32:33], off
	v_subrev_u32_e32 v32, 20, v182
	v_min_i32_e32 v32, s53, v32
	v_mad_u32_u24 v32, v32, v177, v178
	v_add_u32_e32 v33, -8, v32
	v_cmp_lt_i32_e32 vcc, v32, v180
	v_add_u32_e32 v120, v120, v178
	v_add_u32_e32 v209, -8, v120
	v_cndmask_b32_e32 v32, v33, v32, vcc
	v_mad_u32_u24 v32, v32, v141, v130
	v_mov_b32_e32 v33, 0
	v_cndmask_b32_e32 v35, v145, v149, vcc
	v_cndmask_b32_e32 v34, v144, v148, vcc
	v_lshl_add_u64 v[34:35], v[32:33], 2, v[34:35]
	global_load_dwordx4 v[96:99], v[34:35], off
	v_cndmask_b32_e32 v35, v147, v151, vcc
	v_cndmask_b32_e32 v34, v146, v150, vcc
	v_lshl_add_u64 v[32:33], v[32:33], 2, v[34:35]
	global_load_dwordx4 v[100:103], v[32:33], off
	v_add_u32_e32 v32, -16, v182
	v_min_i32_e32 v32, s53, v32
	v_mad_u32_u24 v32, v32, v177, v178
	v_add_u32_e32 v33, -8, v32
	v_cmp_lt_i32_e32 vcc, v32, v180
	v_add_u32_e32 v184, v184, v186
	v_add_u32_e32 v201, v201, v185
	v_cndmask_b32_e32 v32, v33, v32, vcc
	v_mad_u32_u24 v32, v32, v141, v130
	v_mov_b32_e32 v33, 0
	v_cndmask_b32_e32 v35, v145, v149, vcc
	v_cndmask_b32_e32 v34, v144, v148, vcc
	v_lshl_add_u64 v[34:35], v[32:33], 2, v[34:35]
	global_load_dwordx4 v[88:91], v[34:35], off
	v_cndmask_b32_e32 v35, v147, v151, vcc
	v_cndmask_b32_e32 v34, v146, v150, vcc
	v_lshl_add_u64 v[32:33], v[32:33], 2, v[34:35]
	global_load_dwordx4 v[92:95], v[32:33], off
	v_add_u32_e32 v32, -12, v182
	v_min_i32_e32 v32, s53, v32
	v_mad_u32_u24 v32, v32, v177, v178
	v_add_u32_e32 v33, -8, v32
	v_cmp_lt_i32_e32 vcc, v32, v180
	ds_read_b128 v[212:215], v211 offset:32
	v_add_u32_e32 v188, v188, v186
	v_cndmask_b32_e32 v32, v33, v32, vcc
	v_mad_u32_u24 v32, v32, v141, v130
	v_mov_b32_e32 v33, 0
	v_cndmask_b32_e32 v35, v145, v149, vcc
	v_cndmask_b32_e32 v34, v144, v148, vcc
	v_lshl_add_u64 v[34:35], v[32:33], 2, v[34:35]
	global_load_dwordx4 v[80:83], v[34:35], off
	v_cndmask_b32_e32 v35, v147, v151, vcc
	v_cndmask_b32_e32 v34, v146, v150, vcc
	v_lshl_add_u64 v[32:33], v[32:33], 2, v[34:35]
	global_load_dwordx4 v[84:87], v[32:33], off
	v_add_u32_e32 v32, -8, v182
	v_min_i32_e32 v32, s53, v32
	v_mad_u32_u24 v32, v32, v177, v178
	v_add_u32_e32 v33, -8, v32
	v_cmp_lt_i32_e32 vcc, v32, v180
	v_add_u32_e32 v190, v190, v186
	v_add_u32_e32 v192, v192, v186
	v_cndmask_b32_e32 v32, v33, v32, vcc
	v_mad_u32_u24 v32, v32, v141, v130
	v_mov_b32_e32 v33, 0
	v_cndmask_b32_e32 v35, v145, v149, vcc
	v_cndmask_b32_e32 v34, v144, v148, vcc
	v_lshl_add_u64 v[34:35], v[32:33], 2, v[34:35]
	global_load_dwordx4 v[64:67], v[34:35], off
	v_cndmask_b32_e32 v35, v147, v151, vcc
	v_cndmask_b32_e32 v34, v146, v150, vcc
	v_lshl_add_u64 v[32:33], v[32:33], 2, v[34:35]
	global_load_dwordx4 v[68:71], v[32:33], off
	v_add_u32_e32 v32, -4, v182
	v_min_i32_e32 v32, s53, v32
	v_mul_u32_u24_e32 v32, v32, v177
	v_add_u32_e32 v32, v32, v178
	v_add_u32_e32 v33, -8, v32
	v_cmp_lt_i32_e32 vcc, v32, v180
	v_add_u32_e32 v182, 32, v182
	v_add_u32_e32 v194, v194, v186
	v_cndmask_b32_e32 v32, v33, v32, vcc
	v_mul_u32_u24_e32 v32, v32, v141
	v_or_b32_e32 v36, v32, v130
	v_mov_b32_e32 v37, 0
	ds_read_b128 v[32:35], v211
	v_cndmask_b32_e32 v39, v145, v149, vcc
	v_cndmask_b32_e32 v38, v144, v148, vcc
	v_lshlrev_b64 v[76:77], 2, v[36:37]
	v_lshl_add_u64 v[36:37], v[38:39], 0, v[76:77]
	global_load_dwordx4 v[72:75], v[36:37], off
	s_waitcnt lgkmcnt(0)
	v_mfma_f32_32x32x16_bf16 v[32:47], v[32:35], v[56:59], 0
	v_cndmask_b32_e32 v79, v147, v151, vcc
	v_cndmask_b32_e32 v78, v146, v150, vcc
	v_cmp_lt_i32_e32 vcc, v120, v180
	v_lshl_add_u64 v[76:77], v[78:79], 0, v[76:77]
	global_load_dwordx4 v[76:79], v[76:77], off
	v_cndmask_b32_e32 v120, v209, v120, vcc
	v_mul_u32_u24_e32 v220, v120, v141
	v_mfma_f32_32x32x16_bf16 v[32:47], v[212:215], v[60:63], v[32:47]
	ds_read_b128 v[212:215], v211 offset:96
	v_add_u32_e32 v196, v196, v186
	v_add_u32_e32 v198, v198, v186
	v_add_u32_e32 v200, v200, v186
	v_mfma_f32_32x32x16_bf16 v[32:47], v[216:219], v[52:55], v[32:47]
	v_add_u32_e32 v120, s33, v181
	v_cmp_le_u32_e64 s[16:17], v120, v135
	v_or_b32_e32 v218, v220, v130
	v_mov_b32_e32 v219, 0
	v_cndmask_b32_e32 v217, v145, v149, vcc
	s_waitcnt lgkmcnt(0)
	v_mfma_f32_32x32x16_bf16 v[32:47], v[212:215], v[48:51], v[32:47]
	v_cndmask_b32_e32 v216, v144, v148, vcc
	v_lshlrev_b64 v[218:219], 2, v[218:219]
	s_sub_i32 s33, s33, 32
	s_nop 8
	v_cndmask_b32_e64 v210, v173, v32, s[16:17]
	v_add_u32_e32 v32, -1, v120
	v_cmp_le_u32_e64 s[16:17], v32, v135
	s_nop 1
	v_cndmask_b32_e64 v212, v173, v33, s[16:17]
	v_add_u32_e32 v33, -2, v120
	v_cmp_le_u32_e64 s[16:17], v33, v135
	v_add_u32_e32 v33, -3, v120
	v_max3_f32 v32, v210, s90, v212
	v_cndmask_b32_e64 v213, v173, v34, s[16:17]
	v_cmp_le_u32_e64 s[16:17], v33, v135
	v_add_u32_e32 v33, -8, v120
	s_nop 0
	v_cndmask_b32_e64 v214, v173, v35, s[16:17]
	v_cmp_le_u32_e64 s[16:17], v33, v135
	v_add_u32_e32 v33, -9, v120
	v_max3_f32 v32, v32, v213, v214
	v_cndmask_b32_e64 v215, v173, v36, s[16:17]
	v_cmp_le_u32_e64 s[16:17], v33, v135
	v_add_u32_e32 v33, -10, v120
	v_cndmask_b32_e32 v36, v146, v150, vcc
	v_cndmask_b32_e64 v220, v173, v37, s[16:17]
	v_cmp_le_u32_e64 s[16:17], v33, v135
	v_add_u32_e32 v33, -11, v120
	v_max3_f32 v32, v32, v215, v220
	v_cndmask_b32_e64 v221, v173, v38, s[16:17]
	v_cmp_le_u32_e64 s[16:17], v33, v135
	v_add_u32_e32 v33, -16, v120
	v_cndmask_b32_e32 v37, v147, v151, vcc
	v_cndmask_b32_e64 v222, v173, v39, s[16:17]
	v_cmp_le_u32_e64 s[16:17], v33, v135
	v_subrev_u32_e32 v33, 17, v120
	v_max3_f32 v32, v32, v221, v222
	v_cndmask_b32_e64 v40, v173, v40, s[16:17]
	v_cmp_le_u32_e64 s[16:17], v33, v135
	v_subrev_u32_e32 v33, 18, v120
	v_lshl_add_u64 v[36:37], v[36:37], 0, v[218:219]
	v_cndmask_b32_e64 v41, v173, v41, s[16:17]
	v_cmp_le_u32_e64 s[16:17], v33, v135
	v_subrev_u32_e32 v33, 19, v120
	v_max3_f32 v32, v32, v40, v41
	v_cndmask_b32_e64 v42, v173, v42, s[16:17]
	v_cmp_le_u32_e64 s[16:17], v33, v135
	v_subrev_u32_e32 v33, 24, v120
	s_nop 0
	v_cndmask_b32_e64 v43, v173, v43, s[16:17]
	v_cmp_le_u32_e64 s[16:17], v33, v135
	v_subrev_u32_e32 v33, 25, v120
	v_max3_f32 v32, v32, v42, v43
	v_cndmask_b32_e64 v44, v173, v44, s[16:17]
	v_cmp_le_u32_e64 s[16:17], v33, v135
	v_subrev_u32_e32 v33, 26, v120
	s_nop 0
	v_cndmask_b32_e64 v45, v173, v45, s[16:17]
	v_cmp_le_u32_e64 s[16:17], v33, v135
	v_subrev_u32_e32 v33, 27, v120
	v_max3_f32 v32, v32, v44, v45
	v_cndmask_b32_e64 v46, v173, v46, s[16:17]
	v_cmp_le_u32_e64 s[16:17], v33, v135
	s_nop 1
	v_cndmask_b32_e64 v47, v173, v47, s[16:17]
	v_max3_f32 v38, v32, v46, v47
	v_mov_b32_e32 v39, v38
	s_nop 1
	v_permlane32_swap_b32_e32 v39, v38
	v_lshl_add_u64 v[32:33], v[216:217], 0, v[218:219]
	global_load_dwordx4 v[32:35], v[32:33], off
	s_add_i32 s16, s18, s33
	s_cmp_lg_u32 s16, 0
	s_waitcnt lgkmcnt(0)
	v_max3_f32 v209, v208, v38, v39
	v_sub_f32_e32 v38, v210, v209
	v_exp_f32_e32 v210, v38
	global_load_dwordx4 v[36:39], v[36:37], off
	v_sub_f32_e32 v212, v212, v209
	v_exp_f32_e32 v212, v212
	v_sub_f32_e32 v213, v213, v209
	v_exp_f32_e32 v213, v213
	v_sub_f32_e32 v214, v214, v209
	v_exp_f32_e32 v214, v214
	v_sub_f32_e32 v215, v215, v209
	v_sub_f32_e32 v120, v208, v209
	v_add_f32_e32 v208, 0, v210
	v_exp_f32_e32 v215, v215
	v_sub_f32_e32 v216, v220, v209
	v_add_f32_e32 v208, v212, v208
	v_exp_f32_e32 v216, v216
	v_sub_f32_e32 v217, v221, v209
	v_add_f32_e32 v208, v213, v208
	v_exp_f32_e32 v217, v217
	v_sub_f32_e32 v218, v222, v209
	v_add_f32_e32 v208, v214, v208
	v_exp_f32_e32 v218, v218
	v_sub_f32_e32 v40, v40, v209
	v_add_f32_e32 v208, v215, v208
	v_exp_f32_e32 v220, v40
	v_sub_f32_e32 v41, v41, v209
	v_add_f32_e32 v40, v216, v208
	v_exp_f32_e32 v208, v41
	v_sub_f32_e32 v41, v42, v209
	v_add_f32_e32 v40, v217, v40
	v_exp_f32_e32 v221, v41
	v_sub_f32_e32 v41, v43, v209
	v_add_f32_e32 v40, v218, v40
	v_exp_f32_e32 v222, v41
	v_sub_f32_e32 v41, v44, v209
	v_add_f32_e32 v40, v220, v40
	v_exp_f32_e32 v223, v41
	v_sub_f32_e32 v41, v45, v209
	v_add_f32_e32 v40, v208, v40
	v_exp_f32_e32 v224, v41
	v_sub_f32_e32 v41, v46, v209
	v_add_f32_e32 v40, v221, v40
	v_exp_f32_e32 v225, v41
	v_sub_f32_e32 v41, v47, v209
	v_add_f32_e32 v40, v222, v40
	v_exp_f32_e32 v226, v41
	v_add_f32_e32 v40, v223, v40
	v_add_f32_e32 v40, v224, v40
	v_add_f32_e32 v40, v225, v40
	v_exp_f32_e32 v120, v120
	v_add_f32_e32 v227, v226, v40
	ds_read_b64_tr_b16 v[40:41], v175 offset:4608
	ds_read_b64_tr_b16 v[42:43], v175 offset:5760
	v_cvt_pk_bf16_f32 v44, v210, v212
	v_cvt_pk_bf16_f32 v45, v213, v214
	v_cvt_pk_bf16_f32 v46, v215, v216
	v_cvt_pk_bf16_f32 v47, v217, v218
	ds_read_b64_tr_b16 v[212:213], v175 offset:6912
	ds_read_b64_tr_b16 v[214:215], v175 offset:8064
	ds_read_b64_tr_b16 v[218:219], v175 offset:5824
	ds_read_b64_tr_b16 v[216:217], v175 offset:4672
	v_mul_f32_e32 v14, v120, v14
	v_mul_f32_e32 v15, v120, v15
	v_mul_f32_e32 v12, v120, v12
	v_mul_f32_e32 v13, v120, v13
	v_mul_f32_e32 v10, v120, v10
	v_mul_f32_e32 v11, v120, v11
	v_mul_f32_e32 v8, v120, v8
	v_mul_f32_e32 v9, v120, v9
	v_mul_f32_e32 v6, v120, v6
	v_mul_f32_e32 v7, v120, v7
	v_mul_f32_e32 v4, v120, v4
	v_mul_f32_e32 v5, v120, v5
	v_mul_f32_e32 v2, v120, v2
	v_mul_f32_e32 v3, v120, v3
	v_mul_f32_e32 v0, v120, v0
	v_mul_f32_e32 v1, v120, v1
	v_mul_f32_e32 v30, v120, v30
	v_mul_f32_e32 v31, v120, v31
	v_mul_f32_e32 v28, v120, v28
	v_mul_f32_e32 v29, v120, v29
	v_mul_f32_e32 v26, v120, v26
	v_mul_f32_e32 v27, v120, v27
	v_mul_f32_e32 v24, v120, v24
	v_mul_f32_e32 v25, v120, v25
	v_mul_f32_e32 v22, v120, v22
	v_mul_f32_e32 v23, v120, v23
	v_mul_f32_e32 v20, v120, v20
	v_mul_f32_e32 v21, v120, v21
	v_mul_f32_e32 v18, v120, v18
	v_mul_f32_e32 v19, v120, v19
	v_mul_f32_e32 v16, v120, v16
	v_mul_f32_e32 v17, v120, v17
	s_waitcnt lgkmcnt(4)
	v_mfma_f32_32x32x16_bf16 v[0:15], v[40:43], v[44:47], v[0:15]
	v_cvt_pk_bf16_f32 v40, v220, v208
	v_cvt_pk_bf16_f32 v41, v221, v222
	v_cvt_pk_bf16_f32 v42, v223, v224
	ds_read_b64_tr_b16 v[222:223], v175 offset:8128
	ds_read_b64_tr_b16 v[220:221], v175 offset:6976
	v_cvt_pk_bf16_f32 v43, v225, v226
	s_waitcnt lgkmcnt(2)
	v_mfma_f32_32x32x16_bf16 v[16:31], v[216:219], v[44:47], v[16:31]
	v_mov_b32_e32 v44, v227
	s_nop 1
	v_permlane32_swap_b32_e32 v44, v227
	s_waitcnt lgkmcnt(0)
	v_add_f32_e32 v210, v227, v44
	v_fmac_f32_e32 v210, v202, v120
	v_mfma_f32_32x32x16_bf16 v[0:15], v[212:215], v[40:43], v[0:15]
	v_mfma_f32_32x32x16_bf16 v[16:31], v[220:223], v[40:43], v[16:31]
	s_cbranch_scc0 .LBB0_1328
	v_mov_b32_e32 v208, v209
	v_mov_b32_e32 v202, v210
	s_branch .LBB0_1284

.LBB0_1370:
	ds_read_b128 v[32:35], v211
	ds_read_b128 v[64:67], v211 offset:32
	s_waitcnt lgkmcnt(1)
	v_mfma_f32_32x32x16_bf16 v[32:47], v[32:35], v[56:59], 0
	s_waitcnt lgkmcnt(0)
	v_mfma_f32_32x32x16_bf16 v[32:47], v[64:67], v[60:63], v[32:47]
	ds_read_b128 v[56:59], v211 offset:64
	ds_read_b128 v[60:63], v211 offset:96
	v_add_u32_e32 v64, v148, v125
	v_sub_u32_e32 v65, v139, v64
	v_xad_u32 v64, v64, -1, v139
	v_cmp_le_u32_e32 vcc, v65, v135
	v_add_u32_e32 v66, -2, v65
	v_add_u32_e32 v67, -3, v65
	s_waitcnt lgkmcnt(1)
	v_mfma_f32_32x32x16_bf16 v[32:47], v[56:59], v[52:55], v[32:47]
	v_add_u32_e32 v52, -8, v65
	v_add_u32_e32 v53, -9, v65
	v_add_u32_e32 v54, -10, v65
	v_add_u32_e32 v55, -11, v65
	v_add_u32_e32 v56, -16, v65
	v_subrev_u32_e32 v57, 17, v65
	v_subrev_u32_e32 v58, 18, v65
	s_waitcnt lgkmcnt(0)
	v_mfma_f32_32x32x16_bf16 v[32:47], v[60:63], v[48:51], v[32:47]
	v_subrev_u32_e32 v49, 19, v65
	s_nop 10
	v_cndmask_b32_e32 v32, v173, v32, vcc
	v_cmp_le_u32_e32 vcc, v64, v135
	s_nop 1
	v_cndmask_b32_e32 v33, v173, v33, vcc
	v_cmp_le_u32_e32 vcc, v66, v135
	s_nop 1
	v_cndmask_b32_e32 v34, v173, v34, vcc
	v_cmp_le_u32_e32 vcc, v67, v135
	s_nop 1
	v_cndmask_b32_e32 v35, v173, v35, vcc
	v_cmp_le_u32_e32 vcc, v52, v135
	s_nop 1
	v_cndmask_b32_e32 v36, v173, v36, vcc
	v_cmp_le_u32_e32 vcc, v53, v135
	s_nop 1
	v_cndmask_b32_e32 v37, v173, v37, vcc
	v_cmp_le_u32_e32 vcc, v54, v135
	s_nop 1
	v_cndmask_b32_e32 v38, v173, v38, vcc
	v_cmp_le_u32_e32 vcc, v55, v135
	s_nop 1
	v_cndmask_b32_e32 v39, v173, v39, vcc
	v_cmp_le_u32_e32 vcc, v56, v135
	s_nop 1
	v_cndmask_b32_e32 v48, v173, v40, vcc
	v_cmp_le_u32_e32 vcc, v57, v135
	v_max3_f32 v40, v32, s90, v33
	v_max3_f32 v40, v40, v34, v35
	v_cndmask_b32_e32 v41, v173, v41, vcc
	v_cmp_le_u32_e32 vcc, v58, v135
	v_max3_f32 v40, v40, v36, v37
	v_max3_f32 v40, v40, v38, v39
	v_cndmask_b32_e32 v42, v173, v42, vcc
	v_cmp_le_u32_e32 vcc, v49, v135
	v_subrev_u32_e32 v49, 24, v65
	v_max3_f32 v40, v40, v48, v41
	v_cndmask_b32_e32 v43, v173, v43, vcc
	v_cmp_le_u32_e32 vcc, v49, v135
	v_subrev_u32_e32 v49, 25, v65
	v_max3_f32 v40, v40, v42, v43
	v_cndmask_b32_e32 v44, v173, v44, vcc
	v_cmp_le_u32_e32 vcc, v49, v135
	v_subrev_u32_e32 v49, 26, v65
	s_nop 0
	v_cndmask_b32_e32 v45, v173, v45, vcc
	v_cmp_le_u32_e32 vcc, v49, v135
	v_subrev_u32_e32 v49, 27, v65
	v_max3_f32 v40, v40, v44, v45
	v_cndmask_b32_e32 v46, v173, v46, vcc
	v_cmp_le_u32_e32 vcc, v49, v135
	s_nop 1
	v_cndmask_b32_e32 v47, v173, v47, vcc
	v_max3_f32 v40, v40, v46, v47
	v_mov_b32_e32 v49, v40
	s_nop 1
	v_permlane32_swap_b32_e32 v49, v40
	s_waitcnt lgkmcnt(0)
	v_max3_f32 v40, v209, v40, v49
	v_sub_f32_e32 v32, v32, v40
	v_exp_f32_e32 v49, v32
	v_sub_f32_e32 v33, v33, v40
	v_exp_f32_e32 v51, v33
	v_sub_f32_e32 v33, v34, v40
	v_exp_f32_e32 v52, v33
	v_sub_f32_e32 v33, v35, v40
	v_exp_f32_e32 v53, v33
	v_sub_f32_e32 v33, v36, v40
	v_add_f32_e32 v50, 0, v49
	v_exp_f32_e32 v55, v33
	v_sub_f32_e32 v34, v37, v40
	v_add_f32_e32 v33, v51, v50
	v_exp_f32_e32 v50, v34
	v_sub_f32_e32 v34, v38, v40
	v_add_f32_e32 v33, v52, v33
	v_exp_f32_e32 v56, v34
	v_sub_f32_e32 v34, v39, v40
	v_add_f32_e32 v33, v53, v33
	v_exp_f32_e32 v39, v34
	v_sub_f32_e32 v34, v48, v40
	v_add_f32_e32 v33, v55, v33
	v_exp_f32_e32 v57, v34
	v_sub_f32_e32 v34, v41, v40
	v_add_f32_e32 v33, v50, v33
	v_exp_f32_e32 v41, v34
	v_sub_f32_e32 v34, v42, v40
	v_add_f32_e32 v33, v56, v33
	v_exp_f32_e32 v58, v34
	v_sub_f32_e32 v34, v43, v40
	v_add_f32_e32 v33, v39, v33
	v_exp_f32_e32 v59, v34
	v_sub_f32_e32 v34, v44, v40
	v_add_f32_e32 v33, v57, v33
	v_exp_f32_e32 v60, v34
	v_sub_f32_e32 v34, v45, v40
	v_add_f32_e32 v33, v41, v33
	v_exp_f32_e32 v61, v34
	v_sub_f32_e32 v34, v46, v40
	v_add_f32_e32 v33, v58, v33
	v_exp_f32_e32 v62, v34
	v_sub_f32_e32 v34, v47, v40
	v_add_f32_e32 v33, v59, v33
	v_exp_f32_e32 v63, v34
	v_sub_f32_e32 v32, v209, v40
	v_add_f32_e32 v33, v60, v33
	v_exp_f32_e32 v54, v32
	v_add_f32_e32 v32, v61, v33
	v_add_f32_e32 v32, v62, v32
	v_add_f32_e32 v64, v63, v32
	ds_read_b64_tr_b16 v[32:33], v175 offset:4608
	ds_read_b64_tr_b16 v[34:35], v175 offset:5760
	v_cvt_pk_bf16_f32 v36, v49, v51
	ds_read_b64_tr_b16 v[42:43], v175 offset:6912
	ds_read_b64_tr_b16 v[44:45], v175 offset:8064
	ds_read_b64_tr_b16 v[48:49], v175 offset:5824
	ds_read_b64_tr_b16 v[46:47], v175 offset:4672
	v_mul_f32_e32 v14, v54, v14
	v_mul_f32_e32 v15, v54, v15
	v_mul_f32_e32 v12, v54, v12
	v_mul_f32_e32 v13, v54, v13
	v_mul_f32_e32 v10, v54, v10
	v_mul_f32_e32 v11, v54, v11
	v_mul_f32_e32 v8, v54, v8
	v_mul_f32_e32 v9, v54, v9
	v_mul_f32_e32 v6, v54, v6
	v_mul_f32_e32 v7, v54, v7
	v_mul_f32_e32 v4, v54, v4
	v_mul_f32_e32 v5, v54, v5
	v_mul_f32_e32 v2, v54, v2
	v_mul_f32_e32 v3, v54, v3
	v_mul_f32_e32 v0, v54, v0
	v_mul_f32_e32 v1, v54, v1
	v_cvt_pk_bf16_f32 v37, v52, v53
	v_cvt_pk_bf16_f32 v38, v55, v50
	v_cvt_pk_bf16_f32 v39, v56, v39
	v_mul_f32_e32 v30, v54, v30
	v_mul_f32_e32 v31, v54, v31
	v_mul_f32_e32 v28, v54, v28
	v_mul_f32_e32 v29, v54, v29
	v_mul_f32_e32 v26, v54, v26
	v_mul_f32_e32 v27, v54, v27
	v_mul_f32_e32 v24, v54, v24
	v_mul_f32_e32 v25, v54, v25
	v_mul_f32_e32 v22, v54, v22
	v_mul_f32_e32 v23, v54, v23
	v_mul_f32_e32 v20, v54, v20
	v_mul_f32_e32 v21, v54, v21
	v_mul_f32_e32 v18, v54, v18
	v_mul_f32_e32 v19, v54, v19
	v_mul_f32_e32 v16, v54, v16
	v_mul_f32_e32 v17, v54, v17
	s_waitcnt lgkmcnt(4)
	v_mfma_f32_32x32x16_bf16 v[0:15], v[32:35], v[36:39], v[0:15]
	ds_read_b64_tr_b16 v[52:53], v175 offset:8128
	ds_read_b64_tr_b16 v[50:51], v175 offset:6976
	v_cvt_pk_bf16_f32 v32, v57, v41
	v_cvt_pk_bf16_f32 v33, v58, v59
	v_cvt_pk_bf16_f32 v34, v60, v61
	v_cvt_pk_bf16_f32 v35, v62, v63
	s_waitcnt lgkmcnt(2)
	v_mfma_f32_32x32x16_bf16 v[16:31], v[46:49], v[36:39], v[16:31]
	v_mov_b32_e32 v36, v64
	s_nop 1
	v_permlane32_swap_b32_e32 v36, v64
	s_waitcnt lgkmcnt(0)
	v_add_f32_e32 v41, v64, v36
	v_fmac_f32_e32 v41, v210, v54
	v_mfma_f32_32x32x16_bf16 v[0:15], v[42:45], v[32:35], v[0:15]
	v_mfma_f32_32x32x16_bf16 v[16:31], v[50:53], v[32:35], v[16:31]
	v_cmp_ne_u32_e32 vcc, 1, v133
	s_mov_b64 s[8:9], -1
	s_cbranch_vccnz .LBB0_1229
